# P3 tasks of single-batch groups dealt by row block (half-local producers); P3->P4 seam = per-half arrive counter in same-XCC mode; XCC check per half
# baseline (speedup 1.0000x reference)
; __global__ void __launch_bounds__(NWAVES * 64, 2) fwd(Args a) {
;     ...
;         for (int task = xh * cph + gk; task < 64; task += 2 * cph) {
;             int b, h, r0, rows;
;             if (grp < 2) { b = 4 * grp + (task >> 4); h = (task >> 1) & 7; r0 = (task & 1) * 16; rows = 32; }
;             else { b = 8 + (grp - 2); h = task >> 3; r0 = (task & 7) * 16; rows = 128; }
;             const int base = b < 8 ? b * 2048 : NPR + (b - 8) * 8192;
;             const int gbase = base - GROWS * grp;
.LBB0_229:
	s_mov_b64 s[12:13], -1
	s_and_b64 vcc, exec, s[26:27]
	s_cbranch_vccz .LBB0_231
	s_and_b32 s52, s33, 7
	s_mov_b64 s[12:13], 0

; __global__ void __launch_bounds__(NWAVES * 64, 2) fwd(Args a) {
;     ...
;             if (grp < 2) { b = 4 * grp + (task >> 4); h = (task >> 1) & 7; r0 = (task & 1) * 16; rows = 32; }
;             else { b = 8 + (grp - 2); h = task >> 3; r0 = (task & 7) * 16; rows = 128; }
;             const int base = b < 8 ? b * 2048 : NPR + (b - 8) * 8192;
;             const int gbase = base - GROWS * grp;
;             __syncthreads();
;             { const int dr = tid >> 5, dc = tid & 31; tbl[tid] = (dr < 15 && dc < 31) ? a.in[I_RPB][h * 465 + dr * 31 + dc] * 1.4426950408889634f : -1e30f; }
;             if (tid < 64) qgt[tid] = a.in[I_QNG][tid] * a.in[I_KNG][tid];
;             bool sel[4]; int dsel[4]; unsigned psel[2];
;             { const int qc = 16 * j + l15, cs = min(max(qc - 8, 0), 48), o = cs - kc0;
; #pragma unroll
;               for (int e = 0; e < 4; ++e) { const int pp = 4 * fq + e; sel[e] = pp < o; dsel[e] = 4 * (kc0 + pp + (sel[e] ? 16 : 0) - qc + 15); }
;               psel[0] = (sel[0] ? 0u : 0xFFFFu) | (sel[1] ? 0u : 0xFFFF0000u); psel[1] = (sel[2] ? 0u : 0xFFFFu) | (sel[3] ? 0u : 0xFFFF0000u); }
;             const int koff0 = l15 * 128 + 16 * (fq ^ (l15 & 7)), koff1 = l15 * 128 + 16 * ((fq ^ (l15 & 7)) ^ 4);
;             int voff[4];
; #pragma unroll
;             for (int db = 0; db < 4; ++db) voff[db] = (4 * fq + tq) * 128 + 16 * ((2 * db + (tp >> 1)) ^ (4 * (fq & 1) + tq)) + 8 * (tp & 1);
;     ...
;             { const int lo0 = min(max(r0 - 4, 0), rows - 8);
;               for (int kr = lo0; kr < lo0 + 8; ++kr) STAGE_ROW(kr); }
.LBB0_238:
	s_or_b64 exec, exec, s[12:13]
	s_and_b64 s[12:13], exec, s[26:27]
	s_cselect_b32 s12, 1, 4
	s_lshl_b32 s12, s33, s12
	s_lshl_b32 s13, s22, 13
	s_and_b32 s42, s12, s23
	s_lshl_b32 s12, s22, 11
	s_add_i32 s13, s13, 0xffff4000
	s_cmp_lt_i32 s22, 8
	s_cselect_b32 s56, s12, s13
	v_sub_u32_e64 v2, s42, 4 clamp
	s_sub_i32 s12, s56, s61
	v_readfirstlane_b32 s13, v2
	s_lshl_b32 s70, s52, 6
	s_ashr_i32 s53, s52, 31
	s_min_u32 s22, s13, s84
	v_add_u32_e32 v193, s12, v171
	s_ashr_i32 s71, s70, 31
	s_lshl_b64 s[12:13], s[52:53], 17
	s_ashr_i32 s57, s56, 31
	s_add_u32 s23, s91, s12
	s_addc_u32 s28, s92, s13
	s_lshl_b64 s[12:13], s[56:57], 2
	s_add_u32 s12, s23, s12
	s_addc_u32 s13, s28, s13
	s_cmp_eq_u32 s88, 4
	s_cbranch_scc0 .Lrk_skip
	s_lshl_b32 s98, s22, 8
	s_add_u32 s98, s98, 0x100000
	s_add_u32 s98, s12, s98
	s_addc_u32 s99, s13, 0
	global_load_dword v240, v136, s[98:99]
	global_load_dword v241, v136, s[98:99] offset:256
	global_load_dword v242, v136, s[98:99] offset:512
	global_load_dword v243, v136, s[98:99] offset:768
	global_load_dword v244, v136, s[98:99] offset:1024
	global_load_dword v245, v136, s[98:99] offset:1280
	global_load_dword v246, v136, s[98:99] offset:1536
	global_load_dword v247, v136, s[98:99] offset:1792

; __device__ __forceinline__ unsigned xb_ld(unsigned* p)              { return __hip_atomic_load(p, __ATOMIC_RELAXED, __HIP_MEMORY_SCOPE_AGENT); }
; __device__ __forceinline__ unsigned xb_add(unsigned* p, unsigned v) { return __hip_atomic_fetch_add(p, v, __ATOMIC_RELAXED, __HIP_MEMORY_SCOPE_AGENT); }
; #define XB_SPIN(cond, bar) do { unsigned _sp = 0; while (cond) { __builtin_amdgcn_s_sleep(1); \
;     if ((++_sp & 255u) == 0u) { if (xb_ld(&(bar)[XB_TMO])) break; if (_sp > XB_SPIN_CAP) { atomicAdd(&(bar)[XB_TMO], 1u); break; } } } } while (0)
; __device__ __forceinline__ void xcd_barrier(const XcdBarrier& b) {
;     asm volatile("s_waitcnt vmcnt(0)" ::: "memory");
;     __syncthreads();
;     if (threadIdx.x == 0) {
;         unsigned* bar = b.bar;
;         __builtin_amdgcn_s_waitcnt(0);
;         unsigned nloc = b.st[0], nx = b.st[1];
;         if (nloc == 0u) { xcd_barrier_complete(bar, b.x, b.gsize, nloc, nx); b.st[0] = nloc; b.st[1] = nx; }
;         const unsigned old = xb_add(&bar[XB_XSUB(b.x)], 1u);
;         const unsigned gen = old / nloc;
;         if (old + 1u == (gen + 1u) * nloc) {
;             __builtin_amdgcn_fence(__ATOMIC_RELEASE, "agent");
;             asm volatile("s_waitcnt vmcnt(0)" ::: "memory");
;             const unsigned og = xb_add(&bar[XB_TOP], 1u);
;             const unsigned tg = og / nx;
;             if (og + 1u == (tg + 1u) * nx) xb_add(&bar[XB_TOPGEN], 1u);
;             else XB_SPIN(xb_ld(&bar[XB_TOPGEN]) == tg, bar);
;             __builtin_amdgcn_fence(__ATOMIC_ACQUIRE, "agent");
;             xb_add(&bar[XB_XGEN(b.x)], 1u);
;             asm volatile("s_waitcnt vmcnt(0)" ::: "memory");
;         } else {
;             XB_SPIN(xb_ld(&bar[XB_XGEN(b.x)]) == gen, bar);
;             __builtin_amdgcn_fence(__ATOMIC_ACQUIRE, "agent");
;             asm volatile("s_waitcnt vmcnt(0)" ::: "memory");
;         }
;     }
;     __syncthreads();
; }
.LBB0_383:
	s_waitcnt vmcnt(0)
	v_readlane_b32 s90, v250, 11
	v_readlane_b32 s91, v250, 12
	s_waitcnt vmcnt(0) lgkmcnt(0)
	s_barrier
	s_and_saveexec_b64 s[0:1], s[90:91]
	v_readlane_b32 s62, v250, 14
	s_mov_b32 s76, s67
	v_readlane_b32 s66, v250, 38
	v_readlane_b32 s89, v250, 13
	v_readlane_b32 s94, v250, 49
	v_readlane_b32 s95, v250, 48
	v_readlane_b32 s84, v250, 47
	v_readlane_b32 s85, v250, 46
	v_readlane_b32 s63, v250, 15
	v_readlane_b32 s77, v250, 45
	v_readlane_b32 s67, v250, 39
	v_readlane_b32 s60, v250, 44
	s_cbranch_execz .LBB0_435
	s_cmp_lg_u32 s100, 0
	s_cbranch_scc1 .Lq3_slow
	v_readlane_b32 s4, v250, 14
	v_readlane_b32 s5, v250, 15
	s_and_b32 s6, s101, 7
	s_lshl_b32 s6, s6, 7
	s_add_i32 s6, s6, 0x18c00
	v_mov_b32_e32 v1, s6
	v_mov_b32_e32 v2, 1
	s_mov_b32 s9, 0
	s_nop 4
	global_atomic_add v1, v2, s[4:5]
	buffer_inv sc1
.Lq3_spin:
	global_load_dword v3, v1, s[4:5] sc1
	s_waitcnt vmcnt(0)
	v_cmp_gt_u32_e32 vcc, 32, v3
	s_cbranch_vccz .Lq3_ok
	s_sleep 1
	s_add_i32 s9, s9, 1
	s_cmp_lt_u32 s9, 0x2000
	s_cbranch_scc1 .Lq3_spin

; __device__ __forceinline__ unsigned xb_add(unsigned* p, unsigned v) { return __hip_atomic_fetch_add(p, v, __ATOMIC_RELAXED, __HIP_MEMORY_SCOPE_AGENT); }
; __device__ __forceinline__ void xcd_barrier(const XcdBarrier& b) {
;     ...
;     if (threadIdx.x == 0) {
;         unsigned* bar = b.bar;
;         __builtin_amdgcn_s_waitcnt(0);
;         unsigned nloc = b.st[0], nx = b.st[1];
;         if (nloc == 0u) { xcd_barrier_complete(bar, b.x, b.gsize, nloc, nx); b.st[0] = nloc; b.st[1] = nx; }
;         const unsigned old = xb_add(&bar[XB_XSUB(b.x)], 1u);
;         const unsigned gen = old / nloc;
.Lq3_slow:
	s_add_i32 s4, 0, 0x26170
	v_mov_b32_e32 v1, s4
	s_waitcnt vmcnt(0) expcnt(0) lgkmcnt(0)
	ds_read_b32 v3, v1
	s_add_i32 s4, 0, 0x26174
	v_mov_b32_e32 v1, s4
	ds_read_b32 v1, v1
	s_waitcnt lgkmcnt(1)
	v_cmp_ne_u32_e32 vcc, 0, v3
	s_cbranch_vccnz .LBB0_399
	s_add_u32 s4, s34, 0x1000
	s_addc_u32 s5, s35, 0
	s_add_u32 s6, s34, 0x1100
	s_addc_u32 s7, s35, 0
	s_add_u32 s8, s34, 0x1200
	s_addc_u32 s9, s35, 0
	s_add_u32 s10, s34, 0x1300
	s_addc_u32 s11, s35, 0
	s_mov_b32 s14, 1
	v_mov_b32_e32 v17, 0
	s_branch .LBB0_387
